# speedup vs baseline: 1.0064x; 1.0064x over previous
.LBB0_747:
	ds_read_b128 v[136:139], v227 offset:55296
	ds_read_b128 v[140:143], v227 offset:59904
	ds_read_b128 v[148:151], v227 offset:64512
	ds_read_b128 v[152:155], v225 offset:13824
	s_add_i32 s1, s1, 2
	s_min_u32 s2, s1, 0xfc
	v_exp_f32_e32 v180, v112
	v_exp_f32_e32 v181, v80
	v_exp_f32_e32 v80, v113
	v_exp_f32_e32 v0, v81
	s_waitcnt lgkmcnt(3)
	v_mfma_f32_32x32x16_bf16 v[64:79], v[136:139], v[10:13], v[64:79]
	v_add_f32_e32 v81, v180, v181
	v_exp_f32_e32 v182, v114
	v_pk_add_f32 v[14:15], v[80:81], v[0:1]
	v_exp_f32_e32 v183, v82
	v_pk_add_f32 v[14:15], v[14:15], v[14:15] op_sel_hi:[0,1]
	v_exp_f32_e32 v82, v115
	v_exp_f32_e32 v14, v83
	s_waitcnt lgkmcnt(2)
	v_mfma_f32_32x32x16_bf16 v[48:63], v[140:143], v[10:13], v[48:63]
	ds_read_b128 v[136:139], v227 offset:55328
	ds_read_b128 v[156:159], v227 offset:59936
	ds_read_b128 v[228:231], v227 offset:64544
	ds_read_b128 v[232:235], v225 offset:13856
	v_max_i32_e32 v81, v80, v0
	v_add_f32_e32 v83, v182, v183
	s_lshl_b32 s2, s2, 17
	v_max3_i32 v81, v180, v181, v81
	v_max_i32_e32 v114, v182, v183
	s_waitcnt lgkmcnt(5)
	v_mfma_f32_32x32x16_bf16 v[32:47], v[148:151], v[10:13], v[32:47]
	v_add_f32_e64 v112, v82, v14
	v_add_f32_e64 v113, v83, v15
	v_max_i32_e32 v15, v82, v14
	s_add_i32 s42, s2, 0x60000
	v_max3_i32 v15, v81, v114, v15
	v_lshl_add_u64 v[176:177], v[192:193], 0, s[42:43]
	v_lshl_add_u64 v[178:179], v[196:197], 0, s[42:43]
	v_pk_add_f32 v[202:203], v[112:113], v[112:113] op_sel_hi:[0,1]
	s_waitcnt lgkmcnt(4)
	v_mfma_f32_32x32x16_bf16 v[16:31], v[152:155], v[10:13], v[16:31]
	ds_read_b128 v[140:143], v227 offset:55360
	ds_read_b128 v[148:151], v227 offset:59968
	ds_read_b128 v[152:155], v227 offset:64576
	ds_read_b128 v[236:239], v225 offset:13888
	s_waitcnt vmcnt(3)
	ds_write_b128 v221, v[128:131]
	s_waitcnt vmcnt(2)
	ds_write_b128 v221, v[144:147] offset:4608
	s_waitcnt vmcnt(1)
	ds_write_b128 v222, v[168:171] offset:36864
	s_waitcnt vmcnt(0)
	ds_write_b128 v222, v[172:175] offset:46080
	v_add_co_u32_e32 v128, vcc, s33, v200
	global_load_dwordx4 v[10:13], v[176:177], off
	global_load_dwordx4 v[112:115], v[178:179], off
	global_load_dwordx4 v[168:171], v[200:201], off
	v_addc_co_u32_e32 v129, vcc, 0, v201, vcc
	global_load_dwordx4 v[172:175], v[128:129], off
	v_exp_f32_e32 v81, v116
	v_exp_f32_e32 v83, v84
	v_exp_f32_e32 v176, v117
	v_exp_f32_e32 v202, v85
	s_waitcnt lgkmcnt(11)
	v_mfma_f32_32x32x16_bf16 v[64:79], v[136:139], v[6:9], v[64:79]
	v_add_f32_e32 v177, v81, v83
	v_exp_f32_e32 v184, v86
	s_waitcnt lgkmcnt(10)
	v_mfma_f32_32x32x16_bf16 v[48:63], v[156:159], v[6:9], v[48:63]
	s_waitcnt lgkmcnt(9)
	v_mfma_f32_32x32x16_bf16 v[32:47], v[228:231], v[6:9], v[32:47]
	s_waitcnt lgkmcnt(8)
	v_mfma_f32_32x32x16_bf16 v[16:31], v[232:235], v[6:9], v[16:31]
	v_add_f32_e64 v6, v176, v202
	v_add_f32_e64 v7, v177, v203
	v_exp_f32_e32 v177, v118
	v_max_i32_e32 v8, v81, v83
	v_pk_add_f32 v[178:179], v[6:7], v[6:7] op_sel_hi:[0,1]
	v_max_i32_e32 v6, v176, v202
	v_max3_i32 v15, v15, v8, v6
	v_max_i32_e32 v138, v177, v184
	v_add_f32_e32 v207, v177, v184
	v_exp_f32_e32 v206, v119
	v_exp_f32_e32 v178, v87
	s_waitcnt lgkmcnt(7)
	v_mfma_f32_32x32x16_bf16 v[64:79], v[140:143], v[2:5], v[64:79]
	v_exp_f32_e32 v185, v88
	v_exp_f32_e32 v242, v121
	v_pk_add_f32 v[136:137], v[206:207], v[178:179]
	v_exp_f32_e32 v179, v120
	v_pk_add_f32 v[240:241], v[136:137], v[136:137] op_sel_hi:[0,1]
	v_exp_f32_e32 v240, v89
	ds_read_b128 v[6:9], v227 offset:55392
	ds_read_b128 v[128:131], v227 offset:60000
	s_waitcnt lgkmcnt(8)
	v_mfma_f32_32x32x16_bf16 v[48:63], v[148:151], v[2:5], v[48:63]
	ds_read_b128 v[84:87], v227 offset:64608
	ds_read_b128 v[116:119], v225 offset:13920
	v_add_f32_e32 v243, v179, v185
	v_max_i32_e32 v136, v206, v178
	v_add_f32_e64 v88, v242, v240
	v_add_f32_e64 v89, v243, v241
	v_max3_i32 v15, v15, v138, v136
	v_max_i32_e32 v120, v179, v185
	v_pk_add_f32 v[244:245], v[88:89], v[88:89] op_sel_hi:[0,1]
	s_waitcnt lgkmcnt(9)
	v_mfma_f32_32x32x16_bf16 v[32:47], v[152:155], v[2:5], v[32:47]
	v_max_i32_e32 v88, v242, v240
	v_max3_i32 v15, v15, v120, v88
	s_waitcnt lgkmcnt(8)
	v_mfma_f32_32x32x16_bf16 v[16:31], v[236:239], v[2:5], v[16:31]
	s_waitcnt lgkmcnt(3)
	v_mfma_f32_32x32x16_bf16 v[64:79], v[6:9], v[132:135], v[64:79]
	v_exp_f32_e32 v203, v122
	v_exp_f32_e32 v205, v90
	v_exp_f32_e32 v246, v123
	v_exp_f32_e32 v244, v91
	ds_read_b128 v[2:5], v223 offset:18432
	ds_read_b128 v[6:9], v223 offset:18464
	ds_read_b128 v[228:231], v223 offset:23040
	ds_read_b128 v[232:235], v223 offset:23072
	v_exp_f32_e32 v124, v124
	s_waitcnt lgkmcnt(6)
	v_mfma_f32_32x32x16_bf16 v[48:63], v[128:131], v[132:135], v[48:63]
	v_exp_f32_e32 v207, v92
	v_add_f32_e32 v247, v203, v205
	v_max_i32_e32 v88, v203, v205
	v_max_i32_e32 v120, v124, v207
	v_add_f32_e32 v251, v124, v207
	s_waitcnt lgkmcnt(5)
	v_mfma_f32_32x32x16_bf16 v[32:47], v[84:87], v[132:135], v[32:47]
	v_add_f32_e64 v84, v246, v244
	v_add_f32_e64 v85, v247, v245
	v_add_f32_e64 v248, v84, v84
	v_add_f32_e64 v249, v84, v85
	v_max_i32_e32 v84, v246, v244
	v_max3_i32 v15, v15, v88, v84
	s_waitcnt lgkmcnt(4)
	v_mfma_f32_32x32x16_bf16 v[16:31], v[116:119], v[132:135], v[16:31]
	s_waitcnt lgkmcnt(3)
	v_mfma_f32_32x32x16_bf16 v[128:143], v[2:5], v[160:163], v[96:111]
	v_exp_f32_e32 v250, v125
	v_exp_f32_e32 v248, v93
	v_exp_f32_e32 v125, v126
	v_exp_f32_e32 v126, v94
	ds_read_b128 v[2:5], v223 offset:18496
	ds_read_b128 v[84:87], v223 offset:18528
	ds_read_b128 v[88:91], v223 offset:23104
	ds_read_b128 v[236:239], v223 offset:23136
	v_pk_add_f32 v[92:93], v[250:251], v[248:249]
	v_exp_f32_e32 v94, v127
	s_waitcnt lgkmcnt(5)
	v_mfma_f32_32x32x16_bf16 v[144:159], v[228:231], v[160:163], v[96:111]
	v_pk_add_f32 v[92:93], v[92:93], v[92:93] op_sel_hi:[0,1]
	v_exp_f32_e32 v92, v95
	ds_read_b128 v[116:119], v224
	ds_read_b128 v[228:231], v224 offset:1024
	v_add_f32_e32 v95, v125, v126
	v_max_i32_e32 v121, v250, v248
	v_mfma_f32_32x32x16_bf16 v[128:143], v[6:9], v[164:167], v[128:143]
	v_add_f32_e64 v6, v94, v92
	v_add_f32_e64 v7, v95, v93
	v_max3_i32 v8, v15, v120, v121
	v_max_i32_e32 v9, v125, v126
	v_add_f32_e32 v93, v6, v7
	v_max_i32_e32 v6, v94, v92
	v_max3_i32 v15, v8, v9, v6
	s_waitcnt lgkmcnt(6)
	v_mfma_f32_32x32x16_bf16 v[144:159], v[232:235], v[164:167], v[144:159]
	s_waitcnt lgkmcnt(1)
	v_mfma_f32_32x32x16_bf16 v[128:143], v[2:5], v[116:119], v[128:143]
	v_cvt_pk_bf16_f32 v120, v180, v80
	v_cvt_pk_bf16_f32 v121, v182, v82
	v_cvt_pk_bf16_f32 v122, v81, v176
	v_cvt_pk_bf16_f32 v123, v177, v206
	v_cvt_pk_bf16_f32 v6, v181, v0
	v_cvt_pk_bf16_f32 v7, v183, v14
	v_cvt_pk_bf16_f32 v8, v83, v202
	v_mfma_f32_32x32x16_bf16 v[144:159], v[88:91], v[116:119], v[144:159]
	v_cvt_pk_bf16_f32 v116, v179, v242
	v_cvt_pk_bf16_f32 v117, v203, v246
	v_cvt_pk_bf16_f32 v118, v124, v250
	v_cvt_pk_bf16_f32 v119, v125, v94
	v_cvt_pk_bf16_f32 v9, v184, v178
	v_cvt_pk_bf16_f32 v2, v185, v240
	v_cvt_pk_bf16_f32 v3, v205, v244
	s_waitcnt lgkmcnt(0)
	v_cvt_pk_bf16_f32 v4, v207, v248
	v_cvt_pk_bf16_f32 v5, v126, v92
	v_add_f32_e32 v93, v204, v93
	v_cmp_lt_i32_e32 vcc, s64, v15
	s_barrier
	ds_read_b128 v[124:127], v227 offset:36864
	ds_read_b128 v[202:205], v227 offset:41472
	v_mfma_f32_32x32x16_bf16 v[128:143], v[84:87], v[228:231], v[128:143]
	v_mfma_f32_32x32x16_bf16 v[144:159], v[236:239], v[228:231], v[144:159]
	v_mov_b32_e32 v228, v93
	s_cbranch_vccz .LBB0_749
	v_max_i32_e32 v0, 0, v15
	ds_bpermute_b32 v14, v189, v0
	v_and_b32_e32 v15, 0xffff0000, v120
	s_waitcnt lgkmcnt(0)
	v_max_i32_e32 v0, v0, v14
	v_log_f32_e32 v0, v0
	v_lshlrev_b32_e32 v14, 16, v120
	v_max_f32_e32 v81, 0, v0
	v_exp_f32_e64 v0, -v81
	v_add_f32_e32 v226, v226, v81
	v_xor_b32_e32 v80, 0x80000000, v226
	v_sub_f32_e32 v159, v159, v81
	v_pk_mul_f32 v[14:15], v[0:1], v[14:15] op_sel_hi:[0,1]
	v_cvt_pk_bf16_f32 v120, v14, v15
	v_lshlrev_b32_e32 v14, 16, v121
	v_and_b32_e32 v15, 0xffff0000, v121
	v_pk_mul_f32 v[14:15], v[0:1], v[14:15] op_sel_hi:[0,1]
	v_cvt_pk_bf16_f32 v121, v14, v15
	v_lshlrev_b32_e32 v14, 16, v122
	v_and_b32_e32 v15, 0xffff0000, v122
	v_pk_mul_f32 v[14:15], v[0:1], v[14:15] op_sel_hi:[0,1]
	v_cvt_pk_bf16_f32 v122, v14, v15
	v_lshlrev_b32_e32 v14, 16, v123
	v_and_b32_e32 v15, 0xffff0000, v123
	v_pk_mul_f32 v[14:15], v[0:1], v[14:15] op_sel_hi:[0,1]
	v_cvt_pk_bf16_f32 v123, v14, v15
	v_lshlrev_b32_e32 v14, 16, v116
	v_and_b32_e32 v15, 0xffff0000, v116
	v_pk_mul_f32 v[14:15], v[0:1], v[14:15] op_sel_hi:[0,1]
	v_cvt_pk_bf16_f32 v116, v14, v15
	v_lshlrev_b32_e32 v14, 16, v117
	v_and_b32_e32 v15, 0xffff0000, v117
	v_pk_mul_f32 v[14:15], v[0:1], v[14:15] op_sel_hi:[0,1]
	v_cvt_pk_bf16_f32 v117, v14, v15
	v_lshlrev_b32_e32 v14, 16, v118
	v_and_b32_e32 v15, 0xffff0000, v118
	v_pk_mul_f32 v[14:15], v[0:1], v[14:15] op_sel_hi:[0,1]
	v_cvt_pk_bf16_f32 v118, v14, v15
	v_lshlrev_b32_e32 v14, 16, v119
	v_and_b32_e32 v15, 0xffff0000, v119
	v_pk_mul_f32 v[14:15], v[0:1], v[14:15] op_sel_hi:[0,1]
	v_cvt_pk_bf16_f32 v119, v14, v15
	v_lshlrev_b32_e32 v14, 16, v6
	v_and_b32_e32 v15, 0xffff0000, v6
	v_pk_mul_f32 v[14:15], v[0:1], v[14:15] op_sel_hi:[0,1]
	v_cvt_pk_bf16_f32 v6, v14, v15
	v_lshlrev_b32_e32 v14, 16, v7
	v_and_b32_e32 v15, 0xffff0000, v7
	v_pk_mul_f32 v[14:15], v[0:1], v[14:15] op_sel_hi:[0,1]
	v_cvt_pk_bf16_f32 v7, v14, v15
	v_lshlrev_b32_e32 v14, 16, v8
	v_and_b32_e32 v15, 0xffff0000, v8
	v_pk_mul_f32 v[14:15], v[0:1], v[14:15] op_sel_hi:[0,1]
	v_cvt_pk_bf16_f32 v8, v14, v15
	v_lshlrev_b32_e32 v14, 16, v9
	v_and_b32_e32 v15, 0xffff0000, v9
	v_pk_mul_f32 v[14:15], v[0:1], v[14:15] op_sel_hi:[0,1]
	v_cvt_pk_bf16_f32 v9, v14, v15
	v_lshlrev_b32_e32 v14, 16, v2
	v_and_b32_e32 v15, 0xffff0000, v2
	v_pk_mul_f32 v[14:15], v[0:1], v[14:15] op_sel_hi:[0,1]
	v_cvt_pk_bf16_f32 v2, v14, v15
	v_lshlrev_b32_e32 v14, 16, v3
	v_and_b32_e32 v15, 0xffff0000, v3
	v_pk_mul_f32 v[14:15], v[0:1], v[14:15] op_sel_hi:[0,1]
	v_cvt_pk_bf16_f32 v3, v14, v15
	v_lshlrev_b32_e32 v14, 16, v4
	v_and_b32_e32 v15, 0xffff0000, v4
	v_pk_mul_f32 v[14:15], v[0:1], v[14:15] op_sel_hi:[0,1]
	v_cvt_pk_bf16_f32 v4, v14, v15
	v_lshlrev_b32_e32 v14, 16, v5
	v_and_b32_e32 v15, 0xffff0000, v5
	v_pk_mul_f32 v[14:15], v[0:1], v[14:15] op_sel_hi:[0,1]
	v_pk_mul_f32 v[78:79], v[78:79], v[0:1] op_sel_hi:[1,0]
	v_pk_mul_f32 v[76:77], v[76:77], v[0:1] op_sel_hi:[1,0]
	v_pk_mul_f32 v[74:75], v[74:75], v[0:1] op_sel_hi:[1,0]
	v_pk_mul_f32 v[72:73], v[72:73], v[0:1] op_sel_hi:[1,0]
	v_pk_mul_f32 v[70:71], v[70:71], v[0:1] op_sel_hi:[1,0]
	v_pk_mul_f32 v[68:69], v[68:69], v[0:1] op_sel_hi:[1,0]
	v_pk_mul_f32 v[66:67], v[66:67], v[0:1] op_sel_hi:[1,0]
	v_pk_mul_f32 v[64:65], v[64:65], v[0:1] op_sel_hi:[1,0]
	v_pk_mul_f32 v[62:63], v[62:63], v[0:1] op_sel_hi:[1,0]
	v_pk_mul_f32 v[60:61], v[60:61], v[0:1] op_sel_hi:[1,0]
	v_pk_mul_f32 v[58:59], v[58:59], v[0:1] op_sel_hi:[1,0]
	v_pk_mul_f32 v[56:57], v[56:57], v[0:1] op_sel_hi:[1,0]
	v_pk_mul_f32 v[54:55], v[54:55], v[0:1] op_sel_hi:[1,0]
	v_pk_mul_f32 v[52:53], v[52:53], v[0:1] op_sel_hi:[1,0]
	v_pk_mul_f32 v[50:51], v[50:51], v[0:1] op_sel_hi:[1,0]
	v_pk_mul_f32 v[48:49], v[48:49], v[0:1] op_sel_hi:[1,0]
	v_pk_mul_f32 v[46:47], v[46:47], v[0:1] op_sel_hi:[1,0]
	v_pk_mul_f32 v[44:45], v[44:45], v[0:1] op_sel_hi:[1,0]
	v_pk_mul_f32 v[42:43], v[42:43], v[0:1] op_sel_hi:[1,0]
	v_pk_mul_f32 v[40:41], v[40:41], v[0:1] op_sel_hi:[1,0]
	v_pk_mul_f32 v[38:39], v[38:39], v[0:1] op_sel_hi:[1,0]
	v_pk_mul_f32 v[36:37], v[36:37], v[0:1] op_sel_hi:[1,0]
	v_pk_mul_f32 v[34:35], v[34:35], v[0:1] op_sel_hi:[1,0]
	v_pk_mul_f32 v[32:33], v[32:33], v[0:1] op_sel_hi:[1,0]
	v_pk_mul_f32 v[30:31], v[30:31], v[0:1] op_sel_hi:[1,0]
	v_pk_mul_f32 v[28:29], v[28:29], v[0:1] op_sel_hi:[1,0]
	v_pk_mul_f32 v[26:27], v[26:27], v[0:1] op_sel_hi:[1,0]
	v_pk_mul_f32 v[24:25], v[24:25], v[0:1] op_sel_hi:[1,0]
	v_pk_mul_f32 v[22:23], v[22:23], v[0:1] op_sel_hi:[1,0]
	v_pk_mul_f32 v[20:21], v[20:21], v[0:1] op_sel_hi:[1,0]
	v_pk_mul_f32 v[18:19], v[18:19], v[0:1] op_sel_hi:[1,0]
	v_pk_mul_f32 v[16:17], v[16:17], v[0:1] op_sel_hi:[1,0]
	v_sub_f32_e32 v158, v158, v81
	v_sub_f32_e32 v157, v157, v81
	v_sub_f32_e32 v156, v156, v81
	v_sub_f32_e32 v155, v155, v81
	v_sub_f32_e32 v154, v154, v81
	v_sub_f32_e32 v153, v153, v81
	v_sub_f32_e32 v152, v152, v81
	v_sub_f32_e32 v151, v151, v81
	v_sub_f32_e32 v150, v150, v81
	v_sub_f32_e32 v149, v149, v81
	v_sub_f32_e32 v148, v148, v81
	v_sub_f32_e32 v147, v147, v81
	v_sub_f32_e32 v146, v146, v81
	v_sub_f32_e32 v145, v145, v81
	v_sub_f32_e32 v144, v144, v81
	v_cvt_pk_bf16_f32 v5, v14, v15
	v_sub_f32_e32 v143, v143, v81
	v_sub_f32_e32 v142, v142, v81
	v_sub_f32_e32 v141, v141, v81
	v_sub_f32_e32 v140, v140, v81
	v_sub_f32_e32 v139, v139, v81
	v_sub_f32_e32 v138, v138, v81
	v_sub_f32_e32 v137, v137, v81
	v_sub_f32_e32 v136, v136, v81
	v_sub_f32_e32 v135, v135, v81
	v_sub_f32_e32 v134, v134, v81
	v_sub_f32_e32 v133, v133, v81
	v_sub_f32_e32 v132, v132, v81
	v_sub_f32_e32 v131, v131, v81
	v_sub_f32_e32 v130, v130, v81
	v_sub_f32_e32 v129, v129, v81
	v_sub_f32_e32 v128, v128, v81
	v_mul_f32_e32 v228, v228, v0
	v_mov_b32_e32 v81, v80
	v_mov_b32_e32 v82, v80
	v_mov_b32_e32 v83, v80
	v_mov_b32_e32 v84, v80
	v_mov_b32_e32 v85, v80
	v_mov_b32_e32 v86, v80
	v_mov_b32_e32 v87, v80
	v_mov_b32_e32 v88, v80
	v_mov_b32_e32 v89, v80
	v_mov_b32_e32 v90, v80
	v_mov_b32_e32 v91, v80
	v_mov_b32_e32 v92, v80
	v_mov_b32_e32 v93, v80
	v_mov_b32_e32 v94, v80
	v_mov_b32_e32 v95, v80
	v_mov_b32_e32 v96, v80
	v_mov_b32_e32 v97, v80
	v_mov_b32_e32 v98, v80
	v_mov_b32_e32 v99, v80
	v_mov_b32_e32 v100, v80
	v_mov_b32_e32 v101, v80
	v_mov_b32_e32 v102, v80
	v_mov_b32_e32 v103, v80
	v_mov_b32_e32 v104, v80
	v_mov_b32_e32 v105, v80
	v_mov_b32_e32 v106, v80
	v_mov_b32_e32 v107, v80
	v_mov_b32_e32 v108, v80
	v_mov_b32_e32 v109, v80
	v_mov_b32_e32 v110, v80
	v_mov_b32_e32 v111, v80
	s_branch .LBB0_750
.LBB0_749:
.LBB0_750:
	ds_read_b128 v[230:233], v227 offset:46080
	ds_read_b128 v[234:237], v227 offset:50688
	s_min_u32 s2, s1, 0xfb
	s_min_u32 s3, s1, 0xfd
	s_nop 7
	v_exp_f32_e32 v229, v128
	v_exp_f32_e32 v252, v144
	v_exp_f32_e32 v14, v129
	v_exp_f32_e32 v0, v145
	s_waitcnt lgkmcnt(3)
	v_mfma_f32_32x32x16_bf16 v[64:79], v[124:127], v[120:123], v[64:79]
	v_add_f32_e32 v15, v229, v252
	v_exp_f32_e32 v213, v130
	v_pk_add_f32 v[128:129], v[14:15], v[0:1]
	v_exp_f32_e32 v214, v146
	v_exp_f32_e32 v206, v131
	ds_read_b128 v[124:127], v227 offset:36896
	ds_read_b128 v[238:241], v227 offset:41504
	ds_read_b128 v[242:245], v227 offset:46112
	ds_read_b128 v[246:249], v227 offset:50720
	s_waitcnt lgkmcnt(6)
	v_mfma_f32_32x32x16_bf16 v[48:63], v[202:205], v[120:123], v[48:63]
	v_add_f32_e64 v202, v128, v128
	v_add_f32_e64 v203, v128, v129
	v_exp_f32_e32 v202, v147
	v_add_f32_e32 v207, v213, v214
	s_lshl_b32 s2, s2, 17
	v_max_i32_e32 v15, v14, v0
	s_add_i32 s42, s2, 0x80000
	s_lshl_b32 s2, s3, 14
	s_waitcnt lgkmcnt(5)
	v_mfma_f32_32x32x16_bf16 v[32:47], v[230:233], v[120:123], v[32:47]
	v_max3_i32 v15, v229, v252, v15
	v_max_i32_e32 v128, v213, v214
	v_lshl_add_u64 v[250:251], v[192:193], 0, s[42:43]
	v_lshl_add_u64 v[180:181], v[196:197], 0, s[42:43]
	s_add_i32 s42, s2, 0x8000
	v_lshl_add_u64 v[182:183], v[194:195], 0, s[42:43]
	v_lshl_add_u64 v[184:185], v[198:199], 0, s[42:43]
	s_waitcnt lgkmcnt(4)
	v_mfma_f32_32x32x16_bf16 v[16:31], v[234:237], v[120:123], v[16:31]
	v_add_f32_e64 v120, v206, v202
	v_add_f32_e64 v121, v207, v203
	v_add_f32_e64 v204, v120, v120
	v_add_f32_e64 v205, v120, v121
	v_max_i32_e32 v120, v206, v202
	v_max3_i32 v15, v15, v128, v120
	ds_read_b128 v[120:123], v227 offset:36928
	ds_read_b128 v[230:233], v227 offset:41536
	ds_read_b128 v[234:237], v227 offset:46144
	ds_read_b128 v[176:179], v227 offset:50752
	s_waitcnt vmcnt(3)
	ds_write_b128 v221, v[10:13] offset:18432
	s_waitcnt vmcnt(2)
	ds_write_b128 v221, v[112:115] offset:23040
	s_waitcnt vmcnt(1)
	ds_write_b128 v222, v[168:171] offset:55296
	s_waitcnt vmcnt(0)
	ds_write_b128 v222, v[172:175] offset:64512
	global_load_dwordx4 v[128:131], v[250:251], off
	global_load_dwordx4 v[144:147], v[180:181], off
	global_load_dwordx4 v[168:171], v[182:183], off
	global_load_dwordx4 v[172:175], v[184:185], off
	v_exp_f32_e32 v203, v132
	v_exp_f32_e32 v207, v148
	v_exp_f32_e32 v180, v133
	v_exp_f32_e32 v204, v149
	s_waitcnt lgkmcnt(11)
	v_mfma_f32_32x32x16_bf16 v[64:79], v[124:127], v[116:119], v[64:79]
	v_add_f32_e32 v181, v203, v207
	v_max_i32_e32 v12, v203, v207
	v_add_f32_e64 v10, v180, v204
	v_add_f32_e64 v11, v181, v205
	v_exp_f32_e32 v181, v134
	v_exp_f32_e32 v205, v150
	v_pk_add_f32 v[182:183], v[10:11], v[10:11] op_sel_hi:[0,1]
	v_max_i32_e32 v10, v180, v204
	s_waitcnt lgkmcnt(10)
	v_mfma_f32_32x32x16_bf16 v[48:63], v[238:241], v[116:119], v[48:63]
	v_max3_i32 v15, v15, v12, v10
	v_max_i32_e32 v126, v181, v205
	v_add_f32_e32 v185, v181, v205
	s_waitcnt lgkmcnt(9)
	v_mfma_f32_32x32x16_bf16 v[32:47], v[242:245], v[116:119], v[32:47]
	s_waitcnt lgkmcnt(8)
	v_mfma_f32_32x32x16_bf16 v[16:31], v[246:249], v[116:119], v[16:31]
	v_exp_f32_e32 v184, v135
	v_exp_f32_e32 v182, v151
	s_waitcnt lgkmcnt(7)
	v_mfma_f32_32x32x16_bf16 v[64:79], v[120:123], v[6:9], v[64:79]
	ds_read_b128 v[10:13], v227 offset:36960
	ds_read_b128 v[112:115], v227 offset:41568
	ds_read_b128 v[116:119], v227 offset:46176
	ds_read_b128 v[120:123], v227 offset:50784
	v_add_f32_e64 v124, v184, v182
	v_add_f32_e64 v125, v185, v183
	v_exp_f32_e32 v183, v136
	v_exp_f32_e32 v185, v152
	s_waitcnt lgkmcnt(10)
	v_mfma_f32_32x32x16_bf16 v[48:63], v[230:233], v[6:9], v[48:63]
	v_add_f32_e64 v230, v124, v124
	v_add_f32_e64 v231, v124, v125
	v_exp_f32_e32 v232, v137
	v_exp_f32_e32 v230, v153
	v_max_i32_e32 v124, v184, v182
	v_add_f32_e32 v233, v183, v185
	v_max3_i32 v15, v15, v126, v124
	v_pk_add_f32 v[124:125], v[232:233], v[230:231]
	s_waitcnt lgkmcnt(9)
	v_mfma_f32_32x32x16_bf16 v[32:47], v[234:237], v[6:9], v[32:47]
	v_max_i32_e32 v126, v183, v185
	v_add_f32_e64 v234, v124, v124
	v_add_f32_e64 v235, v124, v125
	v_max_i32_e32 v124, v232, v230
	v_max3_i32 v15, v15, v126, v124
	s_waitcnt lgkmcnt(8)
	v_mfma_f32_32x32x16_bf16 v[16:31], v[176:179], v[6:9], v[16:31]
	v_exp_f32_e32 v231, v138
	v_exp_f32_e32 v233, v154
	s_waitcnt lgkmcnt(3)
	v_mfma_f32_32x32x16_bf16 v[64:79], v[10:13], v[2:5], v[64:79]
	v_exp_f32_e32 v236, v139
	v_exp_f32_e32 v234, v155
	ds_read_b128 v[6:9], v223
	ds_read_b128 v[10:13], v223 offset:32
	ds_read_b128 v[132:135], v223 offset:4608
	ds_read_b128 v[148:151], v223 offset:4640
	v_add_f32_e32 v237, v231, v233
	v_exp_f32_e32 v156, v156
	s_waitcnt lgkmcnt(6)
	v_mfma_f32_32x32x16_bf16 v[48:63], v[112:115], v[2:5], v[48:63]
	v_add_f32_e64 v112, v236, v234
	v_add_f32_e64 v113, v237, v235
	v_exp_f32_e32 v235, v140
	v_max_i32_e32 v114, v231, v233
	v_pk_add_f32 v[238:239], v[112:113], v[112:113] op_sel_hi:[0,1]
	v_max_i32_e32 v112, v236, v234
	v_max3_i32 v15, v15, v114, v112
	v_add_f32_e32 v241, v235, v156
	s_waitcnt lgkmcnt(5)
	v_mfma_f32_32x32x16_bf16 v[32:47], v[116:119], v[2:5], v[32:47]
	v_max_i32_e32 v237, v235, v156
	s_waitcnt lgkmcnt(4)
	v_mfma_f32_32x32x16_bf16 v[16:31], v[120:123], v[2:5], v[16:31]
	s_waitcnt lgkmcnt(3)
	v_mfma_f32_32x32x16_bf16 v[112:127], v[6:9], v[160:163], v[96:111]
	v_exp_f32_e32 v240, v141
	v_exp_f32_e32 v238, v157
	v_exp_f32_e32 v158, v158
	ds_read_b128 v[2:5], v223 offset:64
	ds_read_b128 v[136:139], v223 offset:96
	ds_read_b128 v[6:9], v223 offset:4672
	ds_read_b128 v[152:155], v223 offset:4704
	v_pk_add_f32 v[140:141], v[240:241], v[238:239]
	s_nop 0
	v_pk_add_f32 v[140:141], v[140:141], v[140:141] op_sel_hi:[0,1]
	s_waitcnt lgkmcnt(5)
	v_mfma_f32_32x32x16_bf16 v[80:95], v[132:135], v[160:163], v[96:111]
	v_exp_f32_e32 v239, v142
	v_exp_f32_e32 v142, v143
	v_exp_f32_e32 v140, v159
	ds_read_b128 v[132:135], v224
	ds_read_b128 v[176:179], v224 offset:1024
	v_add_f32_e32 v143, v239, v158
	v_max_i32_e32 v157, v240, v238
	v_mfma_f32_32x32x16_bf16 v[112:127], v[10:13], v[164:167], v[112:127]
	v_add_f32_e64 v10, v142, v140
	v_add_f32_e64 v11, v143, v141
	v_max3_i32 v12, v15, v237, v157
	v_max_i32_e32 v13, v239, v158
	v_add_f32_e32 v141, v10, v11
	v_max_i32_e32 v10, v142, v140
	v_max3_i32 v15, v12, v13, v10
	s_waitcnt lgkmcnt(6)
	v_mfma_f32_32x32x16_bf16 v[80:95], v[148:151], v[164:167], v[80:95]
	s_waitcnt lgkmcnt(1)
	v_mfma_f32_32x32x16_bf16 v[112:127], v[2:5], v[132:135], v[112:127]
	v_cvt_pk_bf16_f32 v10, v229, v14
	v_cvt_pk_bf16_f32 v11, v213, v206
	v_cvt_pk_bf16_f32 v12, v203, v180
	v_cvt_pk_bf16_f32 v13, v181, v184
	v_cvt_pk_bf16_f32 v2, v252, v0
	v_cvt_pk_bf16_f32 v3, v214, v202
	v_cvt_pk_bf16_f32 v4, v207, v204
	v_mfma_f32_32x32x16_bf16 v[80:95], v[6:9], v[132:135], v[80:95]
	v_cvt_pk_bf16_f32 v6, v183, v232
	v_cvt_pk_bf16_f32 v7, v231, v236
	v_cvt_pk_bf16_f32 v8, v235, v240
	v_cvt_pk_bf16_f32 v9, v239, v142
	v_cvt_pk_bf16_f32 v5, v205, v182
	v_cvt_pk_bf16_f32 v132, v185, v230
	v_cvt_pk_bf16_f32 v133, v233, v234
	s_waitcnt lgkmcnt(0)
	v_mfma_f32_32x32x16_bf16 v[112:127], v[136:139], v[176:179], v[112:127]
	v_cvt_pk_bf16_f32 v134, v156, v238
	v_cvt_pk_bf16_f32 v135, v158, v140
	v_mfma_f32_32x32x16_bf16 v[80:95], v[152:155], v[176:179], v[80:95]
	v_add_f32_e32 v204, v228, v141
	v_cmp_lt_i32_e32 vcc, s64, v15
	s_barrier
	s_cbranch_vccz .LBB0_746
	v_max_i32_e32 v0, 0, v15
	ds_bpermute_b32 v14, v189, v0
	v_and_b32_e32 v15, 0xffff0000, v10
	s_waitcnt lgkmcnt(0)
	v_max_i32_e32 v0, v0, v14
	v_log_f32_e32 v0, v0
	v_lshlrev_b32_e32 v14, 16, v10
	v_max_f32_e32 v97, 0, v0
	v_exp_f32_e64 v0, -v97
	v_add_f32_e32 v226, v226, v97
	v_xor_b32_e32 v96, 0x80000000, v226
	v_sub_f32_e32 v95, v95, v97
	v_pk_mul_f32 v[14:15], v[0:1], v[14:15] op_sel_hi:[0,1]
	v_cvt_pk_bf16_f32 v10, v14, v15
	v_lshlrev_b32_e32 v14, 16, v11
	v_and_b32_e32 v15, 0xffff0000, v11
	v_pk_mul_f32 v[14:15], v[0:1], v[14:15] op_sel_hi:[0,1]
	v_cvt_pk_bf16_f32 v11, v14, v15
	v_lshlrev_b32_e32 v14, 16, v12
	v_and_b32_e32 v15, 0xffff0000, v12
	v_pk_mul_f32 v[14:15], v[0:1], v[14:15] op_sel_hi:[0,1]
	v_cvt_pk_bf16_f32 v12, v14, v15
	v_lshlrev_b32_e32 v14, 16, v13
	v_and_b32_e32 v15, 0xffff0000, v13
	v_pk_mul_f32 v[14:15], v[0:1], v[14:15] op_sel_hi:[0,1]
	v_cvt_pk_bf16_f32 v13, v14, v15
	v_lshlrev_b32_e32 v14, 16, v6
	v_and_b32_e32 v15, 0xffff0000, v6
	v_pk_mul_f32 v[14:15], v[0:1], v[14:15] op_sel_hi:[0,1]
	v_cvt_pk_bf16_f32 v6, v14, v15
	v_lshlrev_b32_e32 v14, 16, v7
	v_and_b32_e32 v15, 0xffff0000, v7
	v_pk_mul_f32 v[14:15], v[0:1], v[14:15] op_sel_hi:[0,1]
	v_cvt_pk_bf16_f32 v7, v14, v15
	v_lshlrev_b32_e32 v14, 16, v8
	v_and_b32_e32 v15, 0xffff0000, v8
	v_pk_mul_f32 v[14:15], v[0:1], v[14:15] op_sel_hi:[0,1]
	v_cvt_pk_bf16_f32 v8, v14, v15
	v_lshlrev_b32_e32 v14, 16, v9
	v_and_b32_e32 v15, 0xffff0000, v9
	v_pk_mul_f32 v[14:15], v[0:1], v[14:15] op_sel_hi:[0,1]
	v_cvt_pk_bf16_f32 v9, v14, v15
	v_lshlrev_b32_e32 v14, 16, v2
	v_and_b32_e32 v15, 0xffff0000, v2
	v_pk_mul_f32 v[14:15], v[0:1], v[14:15] op_sel_hi:[0,1]
	v_cvt_pk_bf16_f32 v2, v14, v15
	v_lshlrev_b32_e32 v14, 16, v3
	v_and_b32_e32 v15, 0xffff0000, v3
	v_pk_mul_f32 v[14:15], v[0:1], v[14:15] op_sel_hi:[0,1]
	v_cvt_pk_bf16_f32 v3, v14, v15
	v_lshlrev_b32_e32 v14, 16, v4
	v_and_b32_e32 v15, 0xffff0000, v4
	v_pk_mul_f32 v[14:15], v[0:1], v[14:15] op_sel_hi:[0,1]
	v_cvt_pk_bf16_f32 v4, v14, v15
	v_lshlrev_b32_e32 v14, 16, v5
	v_and_b32_e32 v15, 0xffff0000, v5
	v_pk_mul_f32 v[14:15], v[0:1], v[14:15] op_sel_hi:[0,1]
	v_cvt_pk_bf16_f32 v5, v14, v15
	v_lshlrev_b32_e32 v14, 16, v132
	v_and_b32_e32 v15, 0xffff0000, v132
	v_pk_mul_f32 v[14:15], v[0:1], v[14:15] op_sel_hi:[0,1]
	v_cvt_pk_bf16_f32 v132, v14, v15
	v_lshlrev_b32_e32 v14, 16, v133
	v_and_b32_e32 v15, 0xffff0000, v133
	v_pk_mul_f32 v[14:15], v[0:1], v[14:15] op_sel_hi:[0,1]
	v_cvt_pk_bf16_f32 v133, v14, v15
	v_lshlrev_b32_e32 v14, 16, v134
	v_and_b32_e32 v15, 0xffff0000, v134
	v_pk_mul_f32 v[14:15], v[0:1], v[14:15] op_sel_hi:[0,1]
	v_cvt_pk_bf16_f32 v134, v14, v15
	v_lshlrev_b32_e32 v14, 16, v135
	v_and_b32_e32 v15, 0xffff0000, v135
	v_pk_mul_f32 v[14:15], v[0:1], v[14:15] op_sel_hi:[0,1]
	v_pk_mul_f32 v[78:79], v[78:79], v[0:1] op_sel_hi:[1,0]
	v_pk_mul_f32 v[76:77], v[76:77], v[0:1] op_sel_hi:[1,0]
	v_pk_mul_f32 v[74:75], v[74:75], v[0:1] op_sel_hi:[1,0]
	v_pk_mul_f32 v[72:73], v[72:73], v[0:1] op_sel_hi:[1,0]
	v_pk_mul_f32 v[70:71], v[70:71], v[0:1] op_sel_hi:[1,0]
	v_pk_mul_f32 v[68:69], v[68:69], v[0:1] op_sel_hi:[1,0]
	v_pk_mul_f32 v[66:67], v[66:67], v[0:1] op_sel_hi:[1,0]
	v_pk_mul_f32 v[64:65], v[64:65], v[0:1] op_sel_hi:[1,0]
	v_pk_mul_f32 v[62:63], v[62:63], v[0:1] op_sel_hi:[1,0]
	v_pk_mul_f32 v[60:61], v[60:61], v[0:1] op_sel_hi:[1,0]
	v_pk_mul_f32 v[58:59], v[58:59], v[0:1] op_sel_hi:[1,0]
	v_pk_mul_f32 v[56:57], v[56:57], v[0:1] op_sel_hi:[1,0]
	v_pk_mul_f32 v[54:55], v[54:55], v[0:1] op_sel_hi:[1,0]
	v_pk_mul_f32 v[52:53], v[52:53], v[0:1] op_sel_hi:[1,0]
	v_pk_mul_f32 v[50:51], v[50:51], v[0:1] op_sel_hi:[1,0]
	v_pk_mul_f32 v[48:49], v[48:49], v[0:1] op_sel_hi:[1,0]
	v_pk_mul_f32 v[46:47], v[46:47], v[0:1] op_sel_hi:[1,0]
	v_pk_mul_f32 v[44:45], v[44:45], v[0:1] op_sel_hi:[1,0]
	v_pk_mul_f32 v[42:43], v[42:43], v[0:1] op_sel_hi:[1,0]
	v_pk_mul_f32 v[40:41], v[40:41], v[0:1] op_sel_hi:[1,0]
	v_pk_mul_f32 v[38:39], v[38:39], v[0:1] op_sel_hi:[1,0]
	v_pk_mul_f32 v[36:37], v[36:37], v[0:1] op_sel_hi:[1,0]
	v_pk_mul_f32 v[34:35], v[34:35], v[0:1] op_sel_hi:[1,0]
	v_pk_mul_f32 v[32:33], v[32:33], v[0:1] op_sel_hi:[1,0]
	v_pk_mul_f32 v[30:31], v[30:31], v[0:1] op_sel_hi:[1,0]
	v_pk_mul_f32 v[28:29], v[28:29], v[0:1] op_sel_hi:[1,0]
	v_pk_mul_f32 v[26:27], v[26:27], v[0:1] op_sel_hi:[1,0]
	v_pk_mul_f32 v[24:25], v[24:25], v[0:1] op_sel_hi:[1,0]
	v_pk_mul_f32 v[22:23], v[22:23], v[0:1] op_sel_hi:[1,0]
	v_pk_mul_f32 v[20:21], v[20:21], v[0:1] op_sel_hi:[1,0]
	v_pk_mul_f32 v[18:19], v[18:19], v[0:1] op_sel_hi:[1,0]
	v_pk_mul_f32 v[16:17], v[16:17], v[0:1] op_sel_hi:[1,0]
	v_sub_f32_e32 v94, v94, v97
	v_sub_f32_e32 v93, v93, v97
	v_sub_f32_e32 v92, v92, v97
	v_sub_f32_e32 v91, v91, v97
	v_sub_f32_e32 v90, v90, v97
	v_sub_f32_e32 v89, v89, v97
	v_sub_f32_e32 v88, v88, v97
	v_sub_f32_e32 v87, v87, v97
	v_sub_f32_e32 v86, v86, v97
	v_sub_f32_e32 v85, v85, v97
	v_sub_f32_e32 v84, v84, v97
	v_sub_f32_e32 v83, v83, v97
	v_sub_f32_e32 v82, v82, v97
	v_sub_f32_e32 v81, v81, v97
	v_sub_f32_e32 v80, v80, v97
	v_cvt_pk_bf16_f32 v135, v14, v15
	v_sub_f32_e32 v127, v127, v97
	v_sub_f32_e32 v126, v126, v97
	v_sub_f32_e32 v125, v125, v97
	v_sub_f32_e32 v124, v124, v97
	v_sub_f32_e32 v123, v123, v97
	v_sub_f32_e32 v122, v122, v97
	v_sub_f32_e32 v121, v121, v97
	v_sub_f32_e32 v120, v120, v97
	v_sub_f32_e32 v119, v119, v97
	v_sub_f32_e32 v118, v118, v97
	v_sub_f32_e32 v117, v117, v97
	v_sub_f32_e32 v116, v116, v97
	v_sub_f32_e32 v115, v115, v97
	v_sub_f32_e32 v114, v114, v97
	v_sub_f32_e32 v113, v113, v97
	v_sub_f32_e32 v112, v112, v97
	v_mul_f32_e32 v204, v204, v0
	v_mov_b32_e32 v97, v96
	v_mov_b32_e32 v98, v96
	v_mov_b32_e32 v99, v96
	v_mov_b32_e32 v100, v96
	v_mov_b32_e32 v101, v96
	v_mov_b32_e32 v102, v96
	v_mov_b32_e32 v103, v96
	v_mov_b32_e32 v104, v96
	v_mov_b32_e32 v105, v96
	v_mov_b32_e32 v106, v96
	v_mov_b32_e32 v107, v96
	v_mov_b32_e32 v108, v96
	v_mov_b32_e32 v109, v96
	v_mov_b32_e32 v110, v96
	v_mov_b32_e32 v111, v96
	s_branch .LBB0_746
